# plus: units after the first skip the 128-register accumulator zeroing (peeled first iteration uses literal-0 SrcC)
# speedup vs baseline: 1.0248x; 1.0028x over previous
; template <class Epi, class Sched>
; __device__ __forceinline__ void gemm_phase(LAS unsigned char* lds, const int tid, const Sched& S, const Epi& E) {
;     ...
;         const bool has_next = S.next(ui + 1, nxt);
;         const char* nA = has_next ? nxt.A : cA; const char* nB = has_next ? nxt.B : cB;
;         const int nlda = has_next ? nxt.lda : cur.lda, nldb = has_next ? nxt.ldb : cur.ldb;
;         unsigned noffA, noffB;
;         { int t3 = tid; asm volatile("" : "+v"(t3));
;           int R0n, C0n; stage_rc(t3 * 16, R0n, C0n); const int RBn = Epi::PERM ? ((R0n & ~31) + perm32(R0n & 31)) : R0n;
;           noffA = (unsigned)R0n * (unsigned)nlda + (unsigned)C0n * 2u; noffB = (unsigned)RBn * (unsigned)nldb + (unsigned)C0n * 2u; }
;         const int nqA = 64 * nlda, nqB = 64 * nldb, nhA = 128 * nlda, nhB = 128 * nldb;
;     ...
; #pragma unroll
;         for (int a = 0; a < 2; ++a)
; #pragma unroll
;             for (int b = 0; b < 2; ++b)
; #pragma unroll
;                 for (int m = 0; m < 4; ++m)
; #pragma unroll
;                     for (int n = 0; n < 2; ++n) acc[a][b][m][n] = (f32x4){0.f, 0.f, 0.f, 0.f};
.LBB0_171:
	v_mov_b32_e32 v0, v183
	s_and_b64 s[2:3], s[60:61], exec
	v_ashrrev_i32_e32 v3, 31, v0
	v_lshrrev_b32_e32 v3, 26, v3
	v_lshlrev_b32_e32 v2, 4, v0
	v_add_u32_e32 v3, v0, v3
	v_bfe_i32 v0, v0, 27, 1
	v_lshrrev_b32_e32 v0, 22, v0
	v_add_u32_e32 v0, v2, v0
	v_and_b32_e32 v0, 0xfffffc00, v0
	v_sub_u32_e32 v0, v2, v0
	v_lshrrev_b32_e32 v2, 4, v0
	v_bitop3_b32 v0, v2, v0, 32 bitop3:0x6c
	v_ashrrev_i32_e32 v4, 31, v0
	v_ashrrev_i32_e32 v3, 6, v3
	v_lshrrev_b32_e32 v4, 26, v4
	v_lshlrev_b32_e32 v2, 3, v3
	v_add_u32_e32 v4, v0, v4
	v_and_b32_e32 v2, -16, v2
	v_ashrrev_i32_e32 v5, 6, v4
	v_and_b32_e32 v4, 0xc0, v4
	v_add_u32_e32 v2, v5, v2
	v_sub_u32_e32 v0, v0, v4
	v_lshlrev_b32_e32 v3, 5, v3
	v_ashrrev_i16_sdwa v0, v165, sext(v0) dst_sel:DWORD dst_unused:UNUSED_PAD src0_sel:DWORD src1_sel:BYTE_0
	v_lshlrev_b32_e32 v4, 1, v2
	v_lshrrev_b32_e32 v6, 2, v2
	v_and_b32_e32 v5, 3, v5
	s_movk_i32 s2, 0xffe0
	v_and_b32_e32 v3, 32, v3
	v_bfe_i32 v0, v0, 0, 16
	v_and_b32_e32 v4, 24, v4
	v_and_b32_e32 v6, 4, v6
	v_and_or_b32 v5, v2, s2, v5
	s_cselect_b32 s6, s90, s17
	s_cselect_b32 s7, s92, s16
	v_or3_b32 v4, v5, v6, v4
	v_add_lshl_u32 v0, v3, v0, 1
	v_mad_u64_u32 v[130:131], s[2:3], v2, s6, v[0:1]
	v_mad_u64_u32 v[132:133], s[2:3], v4, s7, v[0:1]
	s_lshl_b32 s2, s6, 6
	s_lshl_b32 s18, s7, 6
	s_lshl_b32 s84, s6, 7
	s_lshl_b32 s69, s7, 7
	s_cmp_lt_i32 s37, 1
	s_cbranch_scc1 .LBB0_178
	s_and_b64 s[6:7], s[60:61], exec
	s_cselect_b32 s82, s75, s41
	s_cselect_b32 s48, s74, s40
	s_cselect_b32 s15, s87, s43
	s_cselect_b32 s14, s86, s42
	s_add_i32 s49, s37, -2
	s_ashr_i32 s97, s96, 31
	s_mov_b32 s4, s68
	s_add_u32 s68, s40, s96
	s_addc_u32 s16, s41, s97
	v_mov_b32_e32 v135, v1
	s_ashr_i32 s67, s66, 31
	v_mov_b32_e32 v131, v1
	s_ashr_i32 s3, s2, 31
	s_ashr_i32 s85, s84, 31
	s_mov_b32 s17, 0
	s_cmp_lt_u32 s89, 2
	s_cbranch_scc0 .Lk0_dispatch
	v_mov_b32_e32 v2, 0
	v_mov_b32_e32 v3, v2
	v_mov_b32_e32 v4, v2
	v_mov_b32_e32 v5, v2
	v_mov_b32_e32 v6, v2
	v_mov_b32_e32 v7, v2
	v_mov_b32_e32 v8, v2
	v_mov_b32_e32 v9, v2
	v_mov_b32_e32 v18, v2
	v_mov_b32_e32 v19, v2
	v_mov_b32_e32 v20, v2
	v_mov_b32_e32 v21, v2
	v_mov_b32_e32 v22, v2
	v_mov_b32_e32 v23, v2
	v_mov_b32_e32 v24, v2
	v_mov_b32_e32 v25, v2
	v_mov_b32_e32 v34, v2
	v_mov_b32_e32 v35, v2
	v_mov_b32_e32 v36, v2
	v_mov_b32_e32 v37, v2
	v_mov_b32_e32 v38, v2
	v_mov_b32_e32 v39, v2
	v_mov_b32_e32 v40, v2
	v_mov_b32_e32 v41, v2
	v_mov_b32_e32 v50, v2
	v_mov_b32_e32 v51, v2
	v_mov_b32_e32 v52, v2
	v_mov_b32_e32 v53, v2
	v_mov_b32_e32 v54, v2
	v_mov_b32_e32 v55, v2
	v_mov_b32_e32 v56, v2
	v_mov_b32_e32 v57, v2
	v_mov_b32_e32 v10, v2
	v_mov_b32_e32 v11, v2
	v_mov_b32_e32 v12, v2
	v_mov_b32_e32 v13, v2
	v_mov_b32_e32 v14, v2
	v_mov_b32_e32 v15, v2
	v_mov_b32_e32 v16, v2
	v_mov_b32_e32 v17, v2
	v_mov_b32_e32 v26, v2
	v_mov_b32_e32 v27, v2
	v_mov_b32_e32 v28, v2
	v_mov_b32_e32 v29, v2
	v_mov_b32_e32 v30, v2
	v_mov_b32_e32 v31, v2
	v_mov_b32_e32 v32, v2
	v_mov_b32_e32 v33, v2
	v_mov_b32_e32 v42, v2
	v_mov_b32_e32 v43, v2
	v_mov_b32_e32 v44, v2
	v_mov_b32_e32 v45, v2
	v_mov_b32_e32 v46, v2
	v_mov_b32_e32 v47, v2
	v_mov_b32_e32 v48, v2
	v_mov_b32_e32 v49, v2
	v_mov_b32_e32 v58, v2
	v_mov_b32_e32 v59, v2
	v_mov_b32_e32 v60, v2
	v_mov_b32_e32 v61, v2
	v_mov_b32_e32 v62, v2
	v_mov_b32_e32 v63, v2
	v_mov_b32_e32 v64, v2
	v_mov_b32_e32 v65, v2
	v_mov_b32_e32 v66, v2
	v_mov_b32_e32 v67, v2
	v_mov_b32_e32 v68, v2
	v_mov_b32_e32 v69, v2
	v_mov_b32_e32 v70, v2
	v_mov_b32_e32 v71, v2
	v_mov_b32_e32 v72, v2
	v_mov_b32_e32 v73, v2
	v_mov_b32_e32 v82, v2
	v_mov_b32_e32 v83, v2
	v_mov_b32_e32 v84, v2
	v_mov_b32_e32 v85, v2
	v_mov_b32_e32 v86, v2
	v_mov_b32_e32 v87, v2
	v_mov_b32_e32 v88, v2
	v_mov_b32_e32 v89, v2
	v_mov_b32_e32 v98, v2
	v_mov_b32_e32 v99, v2
	v_mov_b32_e32 v100, v2
	v_mov_b32_e32 v101, v2
	v_mov_b32_e32 v102, v2
	v_mov_b32_e32 v103, v2
	v_mov_b32_e32 v104, v2
	v_mov_b32_e32 v105, v2
	v_mov_b32_e32 v114, v2
	v_mov_b32_e32 v115, v2
	v_mov_b32_e32 v116, v2
	v_mov_b32_e32 v117, v2
	v_mov_b32_e32 v118, v2
	v_mov_b32_e32 v119, v2
	v_mov_b32_e32 v120, v2
	v_mov_b32_e32 v121, v2
	v_mov_b32_e32 v74, v2
	v_mov_b32_e32 v75, v2
	v_mov_b32_e32 v76, v2
	v_mov_b32_e32 v77, v2
	v_mov_b32_e32 v78, v2
	v_mov_b32_e32 v79, v2
	v_mov_b32_e32 v80, v2
	v_mov_b32_e32 v81, v2
	v_mov_b32_e32 v90, v2
	v_mov_b32_e32 v91, v2
	v_mov_b32_e32 v92, v2
	v_mov_b32_e32 v93, v2
	v_mov_b32_e32 v94, v2
	v_mov_b32_e32 v95, v2
	v_mov_b32_e32 v96, v2
	v_mov_b32_e32 v97, v2
	v_mov_b32_e32 v106, v2
	v_mov_b32_e32 v107, v2
	v_mov_b32_e32 v108, v2
	v_mov_b32_e32 v109, v2
	v_mov_b32_e32 v110, v2
	v_mov_b32_e32 v111, v2
	v_mov_b32_e32 v112, v2
	v_mov_b32_e32 v113, v2
	v_mov_b32_e32 v122, v2
	v_mov_b32_e32 v123, v2
	v_mov_b32_e32 v124, v2
	v_mov_b32_e32 v125, v2
	v_mov_b32_e32 v126, v2
	v_mov_b32_e32 v127, v2
	v_mov_b32_e32 v128, v2
	v_mov_b32_e32 v129, v2
	s_branch .LBB0_173
.Lk0_dispatch:
	s_cmp_eq_u32 s5, 1
	s_cbranch_scc1 .Lk0a_head
	s_branch .Lk0b_head

; #define PG8_STAGE(bufoff, gbase, off, q) do { \
;         __builtin_amdgcn_global_load_lds((const unsigned*)((const char*)(gbase) + (off)), (LAS unsigned*)(lds + (bufoff) + ldsw), 16, 0, 0); \
;         __builtin_amdgcn_global_load_lds((const unsigned*)((const char*)(gbase) + (q) + (off)), (LAS unsigned*)(lds + (bufoff) + ldsw + 8192), 16, 0, 0); } while (0)
; #define PG8_LDA(dst, b, h) do { _Pragma("unroll") for (int m = 0; m < 4; ++m) _Pragma("unroll") for (int k = 0; k < 2; ++k) dst[m][k] = *(const LAS bf16x8*)(lds + PG8_SA(b, h) + aoff + m * 2048 + k * 1024); } while (0)
; #define PG8_LDB(dst, b, h) do { _Pragma("unroll") for (int n = 0; n < 2; ++n) _Pragma("unroll") for (int k = 0; k < 2; ++k) dst[n][k] = *(const LAS bf16x8*)(lds + PG8_SB(b, h) + boff + n * 2048 + k * 1024); } while (0)
; #define PG8_MMA(ai, bj, At, Bt) do { __builtin_amdgcn_s_setprio(1); _Pragma("unroll") for (int m = 0; m < 4; ++m) _Pragma("unroll") for (int n = 0; n < 2; ++n) _Pragma("unroll") for (int k = 0; k < 2; ++k) \
;         acc[ai][bj][m][n] = __builtin_amdgcn_mfma_f32_16x16x32_bf16(Bt[n][k], At[m][k], acc[ai][bj][m][n], 0, 0, 0); __builtin_amdgcn_s_setprio(0); } while (0)
; template <class Epi, class Sched>
; __device__ __forceinline__ void gemm_phase(LAS unsigned char* lds, const int tid, const Sched& S, const Epi& E) {
;     ...
;             const bool last = (t == nt - 2);
;             const char* a1 = cA + (size_t)(t + 1) * kstep;
;             const char* a2 = last ? nA : cA + (size_t)(t + 2) * kstep; const char* b2 = last ? nB : cB + (size_t)(t + 2) * kstep;
;             const char* a3 = a2 + kstep; const char* b3 = b2 + kstep;
;             const unsigned oA2 = last ? noffA : offA, oB2 = last ? noffB : offB;
;             const int qA2 = last ? nqA : qA, qB2 = last ? nqB : qB, hA2 = last ? nhA : hA, hB2 = last ? nhB : hB;
;             PG8_LDB(B0, 0, 0); PG8_LDB(B1, 0, 1); PG8_SCHED; PG8_LDA(At, 0, 0); PG8_STAGE(PG8_SA(1, 1), a1 + hA, offA, qA);
;             PG8_WAIT_V(8); PG8_WAIT_L(0); PG8_BAR; PG8_MMA(0, 0, At, B0); PG8_MMA(0, 1, At, B1); PG8_BAR; PG8_SCHED;
;             PG8_LDA(At, 0, 1); PG8_STAGE(PG8_SB(0, 0), b2, oB2, qB2); PG8_STAGE(PG8_SB(0, 1), b2 + hB2, oB2, qB2); PG8_STAGE(PG8_SA(0, 0), a2, oA2, qA2);
;             PG8_WAIT_V(8); PG8_WAIT_L(0); PG8_BAR; PG8_MMA(1, 0, At, B0); PG8_MMA(1, 1, At, B1); PG8_BAR; PG8_SCHED;
.Lk0a_175:
	s_or_b32 vcc_lo, s17, 1
	s_mov_b32 vcc_hi, s21
	s_lshl_b64 s[10:11], vcc, 7
	s_add_u32 s17, s40, s6
	s_addc_u32 vcc_lo, s41, s7
	s_and_b64 s[6:7], exec, s[62:63]
	s_cselect_b32 vcc_hi, s82, vcc_lo
	s_cselect_b32 vcc_lo, s48, s17
	s_add_i32 s17, 0, 0x10000
	v_add_u32_e32 v133, s17, v147
	s_add_i32 s62, 0, 0x14000
	ds_read_b128 v[140:143], v133
	ds_read_b128 v[150:153], v133 offset:1024
	ds_read_b128 v[154:157], v133 offset:2048
	ds_read_b128 v[158:161], v133 offset:3072
	ds_read_b128 v[186:189], v133 offset:16384
	ds_read_b128 v[190:193], v133 offset:17408
	ds_read_b128 v[194:197], v133 offset:18432
	ds_read_b128 v[198:201], v133 offset:19456
	s_add_u32 s6, s68, s10
	s_addc_u32 s7, s16, s11
	s_add_i32 m0, s54, 0xc000
	ds_read_b128 v[202:205], v184
	ds_read_b128 v[206:209], v184 offset:1024
	ds_read_b128 v[210:213], v184 offset:2048
	ds_read_b128 v[214:217], v184 offset:3072
	ds_read_b128 v[218:221], v184 offset:4096
	ds_read_b128 v[222:225], v184 offset:5120
	ds_read_b128 v[226:229], v184 offset:6144
	ds_read_b128 v[230:233], v184 offset:7168
	global_load_lds_dwordx4 v134, s[6:7]
	s_add_u32 s6, s6, s66
	s_addc_u32 s7, s7, s67
	s_add_i32 m0, s54, 0xe000
	s_nop 0
	global_load_lds_dwordx4 v134, s[6:7]
	s_waitcnt vmcnt(16)
	s_waitcnt lgkmcnt(0)
	s_setprio 1
	s_barrier
	v_mfma_f32_16x16x32_bf16 v[126:129], v[140:143], v[202:205], 0
	v_mfma_f32_16x16x32_bf16 v[122:125], v[154:157], v[202:205], 0
	v_mfma_f32_16x16x32_bf16 v[110:113], v[140:143], v[210:213], 0
	v_mfma_f32_16x16x32_bf16 v[106:109], v[154:157], v[210:213], 0
	v_mfma_f32_16x16x32_bf16 v[94:97], v[140:143], v[218:221], 0
	v_mfma_f32_16x16x32_bf16 v[90:93], v[154:157], v[218:221], 0
	v_mfma_f32_16x16x32_bf16 v[78:81], v[140:143], v[226:229], 0
	v_mfma_f32_16x16x32_bf16 v[74:77], v[154:157], v[226:229], 0
	v_mfma_f32_16x16x32_bf16 v[126:129], v[150:153], v[206:209], v[126:129]
	v_mfma_f32_16x16x32_bf16 v[122:125], v[158:161], v[206:209], v[122:125]
	v_mfma_f32_16x16x32_bf16 v[110:113], v[150:153], v[214:217], v[110:113]
	v_mfma_f32_16x16x32_bf16 v[106:109], v[158:161], v[214:217], v[106:109]
	v_mfma_f32_16x16x32_bf16 v[94:97], v[150:153], v[222:225], v[94:97]
	v_mfma_f32_16x16x32_bf16 v[90:93], v[158:161], v[222:225], v[90:93]
	v_mfma_f32_16x16x32_bf16 v[78:81], v[150:153], v[230:233], v[78:81]
	v_mfma_f32_16x16x32_bf16 v[74:77], v[158:161], v[230:233], v[74:77]
	v_mfma_f32_16x16x32_bf16 v[118:121], v[186:189], v[202:205], 0
	v_mfma_f32_16x16x32_bf16 v[114:117], v[194:197], v[202:205], 0
	v_mfma_f32_16x16x32_bf16 v[102:105], v[186:189], v[210:213], 0
	v_mfma_f32_16x16x32_bf16 v[98:101], v[194:197], v[210:213], 0
	v_mfma_f32_16x16x32_bf16 v[86:89], v[186:189], v[218:221], 0
	v_mfma_f32_16x16x32_bf16 v[82:85], v[194:197], v[218:221], 0
	v_mfma_f32_16x16x32_bf16 v[70:73], v[186:189], v[226:229], 0
	v_mfma_f32_16x16x32_bf16 v[66:69], v[194:197], v[226:229], 0
	v_mfma_f32_16x16x32_bf16 v[118:121], v[190:193], v[206:209], v[118:121]
	v_mfma_f32_16x16x32_bf16 v[114:117], v[198:201], v[206:209], v[114:117]
	v_mfma_f32_16x16x32_bf16 v[102:105], v[190:193], v[214:217], v[102:105]
	v_mfma_f32_16x16x32_bf16 v[98:101], v[198:201], v[214:217], v[98:101]
	v_mfma_f32_16x16x32_bf16 v[86:89], v[190:193], v[222:225], v[86:89]
	v_mfma_f32_16x16x32_bf16 v[82:85], v[198:201], v[222:225], v[82:85]
	v_mfma_f32_16x16x32_bf16 v[70:73], v[190:193], v[230:233], v[70:73]
	v_mfma_f32_16x16x32_bf16 v[66:69], v[198:201], v[230:233], v[66:69]
	s_barrier
	s_setprio 0
	s_add_i32 s10, s17, s47
	s_ashr_i32 s11, s73, 31
	s_mov_b32 m0, s10
	s_add_u32 s6, s28, s73
	ds_read_b128 v[202:205], v184 offset:16384
	ds_read_b128 v[206:209], v184 offset:17408
	ds_read_b128 v[210:213], v184 offset:18432
	ds_read_b128 v[214:217], v184 offset:19456
	ds_read_b128 v[218:221], v184 offset:20480
	ds_read_b128 v[222:225], v184 offset:21504
	ds_read_b128 v[226:229], v184 offset:22528
	ds_read_b128 v[230:233], v184 offset:23552
	global_load_lds_dwordx4 v0, s[28:29]
	s_addc_u32 s7, s29, s11
	s_add_i32 m0, s10, 0x2000
	s_nop 0
	global_load_lds_dwordx4 v0, s[6:7]
	s_ashr_i32 s7, s19, 31
	s_add_u32 s6, s28, s19
	s_addc_u32 s7, s29, s7
	s_add_i32 s10, s62, s47
	s_mov_b32 m0, s10
	s_nop 0
	global_load_lds_dwordx4 v0, s[6:7]
	s_add_u32 s6, s6, s73
	s_addc_u32 s7, s7, s11
	s_add_i32 m0, s10, 0x2000
	s_nop 0
	global_load_lds_dwordx4 v0, s[6:7]
	s_add_u32 s6, vcc_lo, s64
	s_mov_b32 m0, s54
	s_addc_u32 s7, vcc_hi, s65
	global_load_lds_dwordx4 v136, vcc
	s_mov_b32 m0, s55
	s_nop 0
	global_load_lds_dwordx4 v136, s[6:7]
	s_waitcnt vmcnt(16)
	s_waitcnt lgkmcnt(0)
	s_setprio 1
	s_barrier
	v_mfma_f32_16x16x32_bf16 v[62:65], v[140:143], v[202:205], 0
	v_mfma_f32_16x16x32_bf16 v[58:61], v[154:157], v[202:205], 0
	v_mfma_f32_16x16x32_bf16 v[46:49], v[140:143], v[210:213], 0
	v_mfma_f32_16x16x32_bf16 v[42:45], v[154:157], v[210:213], 0
	v_mfma_f32_16x16x32_bf16 v[30:33], v[140:143], v[218:221], 0
	v_mfma_f32_16x16x32_bf16 v[26:29], v[154:157], v[218:221], 0
	v_mfma_f32_16x16x32_bf16 v[14:17], v[140:143], v[226:229], 0
	v_mfma_f32_16x16x32_bf16 v[10:13], v[154:157], v[226:229], 0
	v_mfma_f32_16x16x32_bf16 v[62:65], v[150:153], v[206:209], v[62:65]
	v_mfma_f32_16x16x32_bf16 v[58:61], v[158:161], v[206:209], v[58:61]
	v_mfma_f32_16x16x32_bf16 v[46:49], v[150:153], v[214:217], v[46:49]
	v_mfma_f32_16x16x32_bf16 v[42:45], v[158:161], v[214:217], v[42:45]
	v_mfma_f32_16x16x32_bf16 v[30:33], v[150:153], v[222:225], v[30:33]
	v_mfma_f32_16x16x32_bf16 v[26:29], v[158:161], v[222:225], v[26:29]
	v_mfma_f32_16x16x32_bf16 v[14:17], v[150:153], v[230:233], v[14:17]
	v_mfma_f32_16x16x32_bf16 v[10:13], v[158:161], v[230:233], v[10:13]
	v_mfma_f32_16x16x32_bf16 v[54:57], v[186:189], v[202:205], 0
	v_mfma_f32_16x16x32_bf16 v[50:53], v[194:197], v[202:205], 0
	v_mfma_f32_16x16x32_bf16 v[38:41], v[186:189], v[210:213], 0
	v_mfma_f32_16x16x32_bf16 v[34:37], v[194:197], v[210:213], 0
	v_mfma_f32_16x16x32_bf16 v[22:25], v[186:189], v[218:221], 0
	v_mfma_f32_16x16x32_bf16 v[18:21], v[194:197], v[218:221], 0
	v_mfma_f32_16x16x32_bf16 v[6:9], v[186:189], v[226:229], 0
	v_mfma_f32_16x16x32_bf16 v[2:5], v[194:197], v[226:229], 0
	v_mfma_f32_16x16x32_bf16 v[54:57], v[190:193], v[206:209], v[54:57]
	v_mfma_f32_16x16x32_bf16 v[50:53], v[198:201], v[206:209], v[50:53]
	v_mfma_f32_16x16x32_bf16 v[38:41], v[190:193], v[214:217], v[38:41]
	v_mfma_f32_16x16x32_bf16 v[34:37], v[198:201], v[214:217], v[34:37]
	v_mfma_f32_16x16x32_bf16 v[22:25], v[190:193], v[222:225], v[22:25]
	v_mfma_f32_16x16x32_bf16 v[18:21], v[198:201], v[222:225], v[18:21]
	v_mfma_f32_16x16x32_bf16 v[6:9], v[190:193], v[230:233], v[6:9]
	v_mfma_f32_16x16x32_bf16 v[2:5], v[198:201], v[230:233], v[2:5]
	s_barrier
; #define PG8_STAGE(bufoff, gbase, off, q) do { \
;         __builtin_amdgcn_global_load_lds((const unsigned*)((const char*)(gbase) + (off)), (LAS unsigned*)(lds + (bufoff) + ldsw), 16, 0, 0); \
;         __builtin_amdgcn_global_load_lds((const unsigned*)((const char*)(gbase) + (q) + (off)), (LAS unsigned*)(lds + (bufoff) + ldsw + 8192), 16, 0, 0); } while (0)
; #define PG8_LDA(dst, b, h) do { _Pragma("unroll") for (int m = 0; m < 4; ++m) _Pragma("unroll") for (int k = 0; k < 2; ++k) dst[m][k] = *(const LAS bf16x8*)(lds + PG8_SA(b, h) + aoff + m * 2048 + k * 1024); } while (0)
; #define PG8_LDB(dst, b, h) do { _Pragma("unroll") for (int n = 0; n < 2; ++n) _Pragma("unroll") for (int k = 0; k < 2; ++k) dst[n][k] = *(const LAS bf16x8*)(lds + PG8_SB(b, h) + boff + n * 2048 + k * 1024); } while (0)
; #define PG8_MMA(ai, bj, At, Bt) do { __builtin_amdgcn_s_setprio(1); _Pragma("unroll") for (int m = 0; m < 4; ++m) _Pragma("unroll") for (int n = 0; n < 2; ++n) _Pragma("unroll") for (int k = 0; k < 2; ++k) \
;         acc[ai][bj][m][n] = __builtin_amdgcn_mfma_f32_16x16x32_bf16(Bt[n][k], At[m][k], acc[ai][bj][m][n], 0, 0, 0); __builtin_amdgcn_s_setprio(0); } while (0)
; #define PG8_WAIT_V(n) asm volatile("s_waitcnt vmcnt(" #n ")" ::: "memory")
; #define PG8_WAIT_L(n) asm volatile("s_waitcnt lgkmcnt(" #n ")" ::: "memory")
; #define PG8_BAR __builtin_amdgcn_s_barrier()
; #define PG8_SCHED __builtin_amdgcn_sched_barrier(0)
; template <class Epi, class Sched>
; __device__ __forceinline__ void gemm_phase(LAS unsigned char* lds, const int tid, const Sched& S, const Epi& E) {
;     ...
;             PG8_WAIT_V(8); PG8_WAIT_L(0); PG8_BAR; PG8_MMA(1, 0, At, B0); PG8_MMA(1, 1, At, B1); PG8_BAR; PG8_SCHED;
;             PG8_LDB(B0, 1, 0); PG8_LDB(B1, 1, 1); PG8_SCHED; PG8_LDA(At, 1, 0); PG8_STAGE(PG8_SA(0, 1), a2 + hA2, oA2, qA2);
;             PG8_WAIT_V(8); PG8_WAIT_L(0); PG8_BAR; PG8_MMA(0, 0, At, B0); PG8_MMA(0, 1, At, B1); PG8_BAR; PG8_SCHED;
;             PG8_LDA(At, 1, 1); PG8_STAGE(PG8_SB(1, 0), b3, oB2, qB2); PG8_STAGE(PG8_SB(1, 1), b3 + hB2, oB2, qB2); PG8_STAGE(PG8_SA(1, 0), a3, oA2, qA2);
;             PG8_WAIT_V(8); PG8_WAIT_L(0); PG8_BAR; PG8_MMA(1, 0, At, B0); PG8_MMA(1, 1, At, B1); PG8_BAR; PG8_SCHED;
;         }
	s_setprio 0
	s_add_i32 s10, 0, 0x18000
	s_add_i32 s11, 0, 0x1c000
	ds_read_b128 v[140:143], v133 offset:32768
	ds_read_b128 v[150:153], v133 offset:33792
	ds_read_b128 v[154:157], v133 offset:34816
	ds_read_b128 v[158:161], v133 offset:35840
	ds_read_b128 v[186:189], v133 offset:49152
	ds_read_b128 v[190:193], v133 offset:50176
	ds_read_b128 v[194:197], v133 offset:51200
	ds_read_b128 v[198:201], v133 offset:52224
	s_add_u32 s6, vcc_lo, s58
	s_addc_u32 s7, vcc_hi, s59
	s_mov_b32 m0, s91
	ds_read_b128 v[202:205], v184 offset:32768
	ds_read_b128 v[206:209], v184 offset:33792
	ds_read_b128 v[210:213], v184 offset:34816
	ds_read_b128 v[214:217], v184 offset:35840
	ds_read_b128 v[218:221], v184 offset:36864
	ds_read_b128 v[222:225], v184 offset:37888
	ds_read_b128 v[226:229], v184 offset:38912
	ds_read_b128 v[230:233], v184 offset:39936
	global_load_lds_dwordx4 v136, s[6:7]
	s_add_u32 s6, s6, s64
	s_addc_u32 s7, s7, s65
	s_mov_b32 m0, s93
	s_nop 0
	global_load_lds_dwordx4 v136, s[6:7]
	s_waitcnt vmcnt(8)
	s_waitcnt lgkmcnt(0)
	s_setprio 1
	s_barrier
	v_mfma_f32_16x16x32_bf16 v[126:129], v[140:143], v[202:205], v[126:129]
	v_mfma_f32_16x16x32_bf16 v[122:125], v[154:157], v[202:205], v[122:125]
	v_mfma_f32_16x16x32_bf16 v[110:113], v[140:143], v[210:213], v[110:113]
	v_mfma_f32_16x16x32_bf16 v[106:109], v[154:157], v[210:213], v[106:109]
	v_mfma_f32_16x16x32_bf16 v[94:97], v[140:143], v[218:221], v[94:97]
	v_mfma_f32_16x16x32_bf16 v[90:93], v[154:157], v[218:221], v[90:93]
	v_mfma_f32_16x16x32_bf16 v[78:81], v[140:143], v[226:229], v[78:81]
	v_mfma_f32_16x16x32_bf16 v[74:77], v[154:157], v[226:229], v[74:77]
	v_mfma_f32_16x16x32_bf16 v[126:129], v[150:153], v[206:209], v[126:129]
	v_mfma_f32_16x16x32_bf16 v[122:125], v[158:161], v[206:209], v[122:125]
	v_mfma_f32_16x16x32_bf16 v[110:113], v[150:153], v[214:217], v[110:113]
	v_mfma_f32_16x16x32_bf16 v[106:109], v[158:161], v[214:217], v[106:109]
	v_mfma_f32_16x16x32_bf16 v[94:97], v[150:153], v[222:225], v[94:97]
	v_mfma_f32_16x16x32_bf16 v[90:93], v[158:161], v[222:225], v[90:93]
	v_mfma_f32_16x16x32_bf16 v[78:81], v[150:153], v[230:233], v[78:81]
	v_mfma_f32_16x16x32_bf16 v[74:77], v[158:161], v[230:233], v[74:77]
	v_mfma_f32_16x16x32_bf16 v[118:121], v[186:189], v[202:205], v[118:121]
	v_mfma_f32_16x16x32_bf16 v[114:117], v[194:197], v[202:205], v[114:117]
	v_mfma_f32_16x16x32_bf16 v[102:105], v[186:189], v[210:213], v[102:105]
	v_mfma_f32_16x16x32_bf16 v[98:101], v[194:197], v[210:213], v[98:101]
	v_mfma_f32_16x16x32_bf16 v[86:89], v[186:189], v[218:221], v[86:89]
	v_mfma_f32_16x16x32_bf16 v[82:85], v[194:197], v[218:221], v[82:85]
	v_mfma_f32_16x16x32_bf16 v[70:73], v[186:189], v[226:229], v[70:73]
	v_mfma_f32_16x16x32_bf16 v[66:69], v[194:197], v[226:229], v[66:69]
	v_mfma_f32_16x16x32_bf16 v[118:121], v[190:193], v[206:209], v[118:121]
	v_mfma_f32_16x16x32_bf16 v[114:117], v[198:201], v[206:209], v[114:117]
	v_mfma_f32_16x16x32_bf16 v[102:105], v[190:193], v[214:217], v[102:105]
	v_mfma_f32_16x16x32_bf16 v[98:101], v[198:201], v[214:217], v[98:101]
	v_mfma_f32_16x16x32_bf16 v[86:89], v[190:193], v[222:225], v[86:89]
	v_mfma_f32_16x16x32_bf16 v[82:85], v[198:201], v[222:225], v[82:85]
	v_mfma_f32_16x16x32_bf16 v[70:73], v[190:193], v[230:233], v[70:73]
	v_mfma_f32_16x16x32_bf16 v[66:69], v[198:201], v[230:233], v[66:69]
	s_barrier
	s_setprio 0
	s_add_i32 s6, s10, s47
	s_add_i32 m0, s6, 0xffffff80
	ds_read_b128 v[202:205], v184 offset:49152
	ds_read_b128 v[206:209], v184 offset:50176
	ds_read_b128 v[210:213], v184 offset:51200
	ds_read_b128 v[214:217], v184 offset:52224
	ds_read_b128 v[218:221], v184 offset:53248
	ds_read_b128 v[222:225], v184 offset:54272
	ds_read_b128 v[226:229], v184 offset:55296
	ds_read_b128 v[230:233], v184 offset:56320
	global_load_lds_dwordx4 v0, s[28:29] offset:128
	s_add_i32 m0, s6, 0x1f80
	s_add_i32 s6, s11, s47
	s_ashr_i32 s100, s73, 31
	s_add_u32 s98, s28, s73
	s_addc_u32 s99, s29, s100
	global_load_lds_dwordx4 v0, s[98:99] offset:128
	s_add_i32 m0, s6, 0xffffff80
	s_nop 0
	s_ashr_i32 s101, s19, 31
	s_add_u32 s98, s28, s19
	s_addc_u32 s99, s29, s101
	global_load_lds_dwordx4 v0, s[98:99] offset:128
	s_add_i32 m0, s6, 0x1f80
	s_nop 0
	s_add_u32 s98, s98, s73
	s_addc_u32 s99, s99, s100
	global_load_lds_dwordx4 v0, s[98:99] offset:128
	s_add_i32 m0, s77, 0xffffff80
	s_nop 0
	global_load_lds_dwordx4 v136, vcc offset:128
	s_add_i32 m0, s88, 0xffffff80
	s_nop 0
	s_add_u32 s98, vcc_lo, s64
	s_addc_u32 s99, vcc_hi, s65
	global_load_lds_dwordx4 v136, s[98:99] offset:128
	s_waitcnt vmcnt(8)
	s_waitcnt lgkmcnt(0)
	s_setprio 1
	s_barrier
	v_mfma_f32_16x16x32_bf16 v[62:65], v[140:143], v[202:205], v[62:65]
	v_mfma_f32_16x16x32_bf16 v[58:61], v[154:157], v[202:205], v[58:61]
	v_mfma_f32_16x16x32_bf16 v[46:49], v[140:143], v[210:213], v[46:49]
	v_mfma_f32_16x16x32_bf16 v[42:45], v[154:157], v[210:213], v[42:45]
	v_mfma_f32_16x16x32_bf16 v[30:33], v[140:143], v[218:221], v[30:33]
	v_mfma_f32_16x16x32_bf16 v[26:29], v[154:157], v[218:221], v[26:29]
	v_mfma_f32_16x16x32_bf16 v[14:17], v[140:143], v[226:229], v[14:17]
	v_mfma_f32_16x16x32_bf16 v[10:13], v[154:157], v[226:229], v[10:13]
	v_mfma_f32_16x16x32_bf16 v[62:65], v[150:153], v[206:209], v[62:65]
	v_mfma_f32_16x16x32_bf16 v[58:61], v[158:161], v[206:209], v[58:61]
	v_mfma_f32_16x16x32_bf16 v[46:49], v[150:153], v[214:217], v[46:49]
	v_mfma_f32_16x16x32_bf16 v[42:45], v[158:161], v[214:217], v[42:45]
	v_mfma_f32_16x16x32_bf16 v[30:33], v[150:153], v[222:225], v[30:33]
	v_mfma_f32_16x16x32_bf16 v[26:29], v[158:161], v[222:225], v[26:29]
	v_mfma_f32_16x16x32_bf16 v[14:17], v[150:153], v[230:233], v[14:17]
	v_mfma_f32_16x16x32_bf16 v[10:13], v[158:161], v[230:233], v[10:13]
	v_mfma_f32_16x16x32_bf16 v[54:57], v[186:189], v[202:205], v[54:57]
	v_mfma_f32_16x16x32_bf16 v[50:53], v[194:197], v[202:205], v[50:53]
	v_mfma_f32_16x16x32_bf16 v[38:41], v[186:189], v[210:213], v[38:41]
	v_mfma_f32_16x16x32_bf16 v[34:37], v[194:197], v[210:213], v[34:37]
	v_mfma_f32_16x16x32_bf16 v[22:25], v[186:189], v[218:221], v[22:25]
	v_mfma_f32_16x16x32_bf16 v[18:21], v[194:197], v[218:221], v[18:21]
	v_mfma_f32_16x16x32_bf16 v[6:9], v[186:189], v[226:229], v[6:9]
	v_mfma_f32_16x16x32_bf16 v[2:5], v[194:197], v[226:229], v[2:5]
	v_mfma_f32_16x16x32_bf16 v[54:57], v[190:193], v[206:209], v[54:57]
	v_mfma_f32_16x16x32_bf16 v[50:53], v[198:201], v[206:209], v[50:53]
	v_mfma_f32_16x16x32_bf16 v[38:41], v[190:193], v[214:217], v[38:41]
	v_mfma_f32_16x16x32_bf16 v[34:37], v[198:201], v[214:217], v[34:37]
	v_mfma_f32_16x16x32_bf16 v[22:25], v[190:193], v[222:225], v[22:25]
	v_mfma_f32_16x16x32_bf16 v[18:21], v[198:201], v[222:225], v[18:21]
	v_mfma_f32_16x16x32_bf16 v[6:9], v[190:193], v[230:233], v[6:9]
	v_mfma_f32_16x16x32_bf16 v[2:5], v[198:201], v[230:233], v[2:5]
	s_barrier
	s_setprio 0
	s_cmp_ge_i32 s20, s37
	s_cbranch_scc1 .LBB0_177
	s_mov_b32 s17, s20
	s_branch .LBB0_173

; #define PG8_STAGE(bufoff, gbase, off, q) do { \
;         __builtin_amdgcn_global_load_lds((const unsigned*)((const char*)(gbase) + (off)), (LAS unsigned*)(lds + (bufoff) + ldsw), 16, 0, 0); \
;         __builtin_amdgcn_global_load_lds((const unsigned*)((const char*)(gbase) + (q) + (off)), (LAS unsigned*)(lds + (bufoff) + ldsw + 8192), 16, 0, 0); } while (0)
; #define PG8_LDA(dst, b, h) do { _Pragma("unroll") for (int m = 0; m < 4; ++m) _Pragma("unroll") for (int k = 0; k < 2; ++k) dst[m][k] = *(const LAS bf16x8*)(lds + PG8_SA(b, h) + aoff + m * 2048 + k * 1024); } while (0)
; #define PG8_LDB(dst, b, h) do { _Pragma("unroll") for (int n = 0; n < 2; ++n) _Pragma("unroll") for (int k = 0; k < 2; ++k) dst[n][k] = *(const LAS bf16x8*)(lds + PG8_SB(b, h) + boff + n * 2048 + k * 1024); } while (0)
; #define PG8_MMA(ai, bj, At, Bt) do { __builtin_amdgcn_s_setprio(1); _Pragma("unroll") for (int m = 0; m < 4; ++m) _Pragma("unroll") for (int n = 0; n < 2; ++n) _Pragma("unroll") for (int k = 0; k < 2; ++k) \
;         acc[ai][bj][m][n] = __builtin_amdgcn_mfma_f32_16x16x32_bf16(Bt[n][k], At[m][k], acc[ai][bj][m][n], 0, 0, 0); __builtin_amdgcn_s_setprio(0); } while (0)
; #define PG8_WAIT_V(n) asm volatile("s_waitcnt vmcnt(" #n ")" ::: "memory")
; #define PG8_WAIT_L(n) asm volatile("s_waitcnt lgkmcnt(" #n ")" ::: "memory")
; #define PG8_BAR __builtin_amdgcn_s_barrier()
; #define PG8_SCHED __builtin_amdgcn_sched_barrier(0)
; template <class Epi, class Sched>
; __device__ __forceinline__ void gemm_phase(LAS unsigned char* lds, const int tid, const Sched& S, const Epi& E) {
;     ...
;             PG8_LDB(B0, 0, 0); PG8_LDB(B1, 0, 1); PG8_SCHED; PG8_LDA(At, 0, 0); PG8_STAGE(PG8_SA(1, 1), a1 + hA, offA, qA);
;             PG8_WAIT_V(8); PG8_WAIT_L(0); PG8_BAR; PG8_MMA(0, 0, At, B0); PG8_MMA(0, 1, At, B1); PG8_BAR; PG8_SCHED;
;             PG8_LDA(At, 0, 1); PG8_STAGE(PG8_SB(0, 0), b2, oB2, qB2); PG8_STAGE(PG8_SB(0, 1), b2 + hB2, oB2, qB2); PG8_STAGE(PG8_SA(0, 0), a2, oA2, qA2);
;             PG8_WAIT_V(8); PG8_WAIT_L(0); PG8_BAR; PG8_MMA(1, 0, At, B0); PG8_MMA(1, 1, At, B1); PG8_BAR; PG8_SCHED;
;     ...
; #pragma unroll
;         for (int a = 0; a < 2; ++a)
; #pragma unroll
;             for (int b = 0; b < 2; ++b)
; #pragma unroll
;                 for (int m = 0; m < 4; ++m)
; #pragma unroll
;                     for (int n = 0; n < 2; ++n) acc[a][b][m][n] = (f32x4){0.f, 0.f, 0.f, 0.f};
.Lk0b_175:
	s_or_b32 vcc_lo, s17, 1
	s_mov_b32 vcc_hi, s21
	s_lshl_b64 s[10:11], vcc, 7
	s_add_u32 s17, s40, s6
	s_addc_u32 vcc_lo, s41, s7
	s_and_b64 s[6:7], exec, s[62:63]
	s_cselect_b32 vcc_hi, s82, vcc_lo
	s_cselect_b32 vcc_lo, s48, s17
	s_add_i32 s17, 0, 0x10000
	v_add_u32_e32 v133, s17, v147
	s_add_i32 s62, 0, 0x14000
	ds_read_b128 v[140:143], v133
	ds_read_b128 v[150:153], v133 offset:1024
	ds_read_b128 v[154:157], v133 offset:2048
	ds_read_b128 v[158:161], v133 offset:3072
	ds_read_b128 v[186:189], v133 offset:16384
	ds_read_b128 v[190:193], v133 offset:17408
	ds_read_b128 v[194:197], v133 offset:18432
	ds_read_b128 v[198:201], v133 offset:19456
	s_add_u32 s6, s68, s10
	s_addc_u32 s7, s16, s11
	s_add_i32 m0, s54, 0xc000
	ds_read_b128 v[202:205], v184
	ds_read_b128 v[206:209], v184 offset:1024
	ds_read_b128 v[210:213], v184 offset:2048
	ds_read_b128 v[214:217], v184 offset:3072
	ds_read_b128 v[218:221], v184 offset:4096
	ds_read_b128 v[222:225], v184 offset:5120
	ds_read_b128 v[226:229], v184 offset:6144
	ds_read_b128 v[230:233], v184 offset:7168
	global_load_lds_dwordx4 v134, s[6:7]
	s_add_u32 s6, s6, s66
	s_addc_u32 s7, s7, s67
	s_add_i32 m0, s54, 0xe000
	s_nop 0
	global_load_lds_dwordx4 v134, s[6:7]
	s_waitcnt vmcnt(24)
	s_waitcnt lgkmcnt(0)
	s_setprio 1
	s_barrier
	v_mfma_f32_16x16x32_bf16 v[126:129], v[140:143], v[202:205], 0
	v_mfma_f32_16x16x32_bf16 v[122:125], v[154:157], v[202:205], 0
	v_mfma_f32_16x16x32_bf16 v[110:113], v[140:143], v[210:213], 0
	v_mfma_f32_16x16x32_bf16 v[106:109], v[154:157], v[210:213], 0
	v_mfma_f32_16x16x32_bf16 v[94:97], v[140:143], v[218:221], 0
	v_mfma_f32_16x16x32_bf16 v[90:93], v[154:157], v[218:221], 0
	v_mfma_f32_16x16x32_bf16 v[78:81], v[140:143], v[226:229], 0
	v_mfma_f32_16x16x32_bf16 v[74:77], v[154:157], v[226:229], 0
	v_mfma_f32_16x16x32_bf16 v[126:129], v[150:153], v[206:209], v[126:129]
	v_mfma_f32_16x16x32_bf16 v[122:125], v[158:161], v[206:209], v[122:125]
	v_mfma_f32_16x16x32_bf16 v[110:113], v[150:153], v[214:217], v[110:113]
	v_mfma_f32_16x16x32_bf16 v[106:109], v[158:161], v[214:217], v[106:109]
	v_mfma_f32_16x16x32_bf16 v[94:97], v[150:153], v[222:225], v[94:97]
	v_mfma_f32_16x16x32_bf16 v[90:93], v[158:161], v[222:225], v[90:93]
	v_mfma_f32_16x16x32_bf16 v[78:81], v[150:153], v[230:233], v[78:81]
	v_mfma_f32_16x16x32_bf16 v[74:77], v[158:161], v[230:233], v[74:77]
	v_mfma_f32_16x16x32_bf16 v[118:121], v[186:189], v[202:205], 0
	v_mfma_f32_16x16x32_bf16 v[114:117], v[194:197], v[202:205], 0
	v_mfma_f32_16x16x32_bf16 v[102:105], v[186:189], v[210:213], 0
	v_mfma_f32_16x16x32_bf16 v[98:101], v[194:197], v[210:213], 0
	v_mfma_f32_16x16x32_bf16 v[86:89], v[186:189], v[218:221], 0
	v_mfma_f32_16x16x32_bf16 v[82:85], v[194:197], v[218:221], 0
	v_mfma_f32_16x16x32_bf16 v[70:73], v[186:189], v[226:229], 0
	v_mfma_f32_16x16x32_bf16 v[66:69], v[194:197], v[226:229], 0
	v_mfma_f32_16x16x32_bf16 v[118:121], v[190:193], v[206:209], v[118:121]
	v_mfma_f32_16x16x32_bf16 v[114:117], v[198:201], v[206:209], v[114:117]
	v_mfma_f32_16x16x32_bf16 v[102:105], v[190:193], v[214:217], v[102:105]
	v_mfma_f32_16x16x32_bf16 v[98:101], v[198:201], v[214:217], v[98:101]
	v_mfma_f32_16x16x32_bf16 v[86:89], v[190:193], v[222:225], v[86:89]
	v_mfma_f32_16x16x32_bf16 v[82:85], v[198:201], v[222:225], v[82:85]
	v_mfma_f32_16x16x32_bf16 v[70:73], v[190:193], v[230:233], v[70:73]
	v_mfma_f32_16x16x32_bf16 v[66:69], v[198:201], v[230:233], v[66:69]
	s_barrier
	s_setprio 0
	s_add_i32 s10, s17, s47
	s_ashr_i32 s11, s73, 31
	s_mov_b32 m0, s10
	s_add_u32 s6, s28, s73
	ds_read_b128 v[202:205], v184 offset:16384
	ds_read_b128 v[206:209], v184 offset:17408
	ds_read_b128 v[210:213], v184 offset:18432
	ds_read_b128 v[214:217], v184 offset:19456
	ds_read_b128 v[218:221], v184 offset:20480
	ds_read_b128 v[222:225], v184 offset:21504
	ds_read_b128 v[226:229], v184 offset:22528
	ds_read_b128 v[230:233], v184 offset:23552
	global_load_lds_dwordx4 v0, s[28:29]
	s_addc_u32 s7, s29, s11
	s_add_i32 m0, s10, 0x2000
	s_nop 0
	global_load_lds_dwordx4 v0, s[6:7]
	s_ashr_i32 s7, s19, 31
	s_add_u32 s6, s28, s19
	s_addc_u32 s7, s29, s7
	s_add_i32 s10, s62, s47
	s_mov_b32 m0, s10
	s_nop 0
	global_load_lds_dwordx4 v0, s[6:7]
	s_add_u32 s6, s6, s73
	s_addc_u32 s7, s7, s11
	s_add_i32 m0, s10, 0x2000
	s_nop 0
	global_load_lds_dwordx4 v0, s[6:7]
	s_add_u32 s6, vcc_lo, s64
	s_mov_b32 m0, s54
	s_addc_u32 s7, vcc_hi, s65
	global_load_lds_dwordx4 v136, vcc
	s_mov_b32 m0, s55
	s_nop 0
	global_load_lds_dwordx4 v136, s[6:7]
	s_waitcnt vmcnt(24)
	s_waitcnt lgkmcnt(0)
	s_setprio 1
	s_barrier
	v_mfma_f32_16x16x32_bf16 v[62:65], v[140:143], v[202:205], 0
	v_mfma_f32_16x16x32_bf16 v[58:61], v[154:157], v[202:205], 0
	v_mfma_f32_16x16x32_bf16 v[46:49], v[140:143], v[210:213], 0
	v_mfma_f32_16x16x32_bf16 v[42:45], v[154:157], v[210:213], 0
	v_mfma_f32_16x16x32_bf16 v[30:33], v[140:143], v[218:221], 0
	v_mfma_f32_16x16x32_bf16 v[26:29], v[154:157], v[218:221], 0
	v_mfma_f32_16x16x32_bf16 v[14:17], v[140:143], v[226:229], 0
	v_mfma_f32_16x16x32_bf16 v[10:13], v[154:157], v[226:229], 0
	v_mfma_f32_16x16x32_bf16 v[62:65], v[150:153], v[206:209], v[62:65]
	v_mfma_f32_16x16x32_bf16 v[58:61], v[158:161], v[206:209], v[58:61]
	v_mfma_f32_16x16x32_bf16 v[46:49], v[150:153], v[214:217], v[46:49]
	v_mfma_f32_16x16x32_bf16 v[42:45], v[158:161], v[214:217], v[42:45]
	v_mfma_f32_16x16x32_bf16 v[30:33], v[150:153], v[222:225], v[30:33]
	v_mfma_f32_16x16x32_bf16 v[26:29], v[158:161], v[222:225], v[26:29]
	v_mfma_f32_16x16x32_bf16 v[14:17], v[150:153], v[230:233], v[14:17]
	v_mfma_f32_16x16x32_bf16 v[10:13], v[158:161], v[230:233], v[10:13]
	v_mfma_f32_16x16x32_bf16 v[54:57], v[186:189], v[202:205], 0
	v_mfma_f32_16x16x32_bf16 v[50:53], v[194:197], v[202:205], 0
	v_mfma_f32_16x16x32_bf16 v[38:41], v[186:189], v[210:213], 0
	v_mfma_f32_16x16x32_bf16 v[34:37], v[194:197], v[210:213], 0
	v_mfma_f32_16x16x32_bf16 v[22:25], v[186:189], v[218:221], 0
	v_mfma_f32_16x16x32_bf16 v[18:21], v[194:197], v[218:221], 0
	v_mfma_f32_16x16x32_bf16 v[6:9], v[186:189], v[226:229], 0
	v_mfma_f32_16x16x32_bf16 v[2:5], v[194:197], v[226:229], 0
	v_mfma_f32_16x16x32_bf16 v[54:57], v[190:193], v[206:209], v[54:57]
	v_mfma_f32_16x16x32_bf16 v[50:53], v[198:201], v[206:209], v[50:53]
	v_mfma_f32_16x16x32_bf16 v[38:41], v[190:193], v[214:217], v[38:41]
	v_mfma_f32_16x16x32_bf16 v[34:37], v[198:201], v[214:217], v[34:37]
	v_mfma_f32_16x16x32_bf16 v[22:25], v[190:193], v[222:225], v[22:25]
	v_mfma_f32_16x16x32_bf16 v[18:21], v[198:201], v[222:225], v[18:21]
	v_mfma_f32_16x16x32_bf16 v[6:9], v[190:193], v[230:233], v[6:9]
	v_mfma_f32_16x16x32_bf16 v[2:5], v[198:201], v[230:233], v[2:5]
	s_barrier
; #define PG8_STAGE(bufoff, gbase, off, q) do { \
;         __builtin_amdgcn_global_load_lds((const unsigned*)((const char*)(gbase) + (off)), (LAS unsigned*)(lds + (bufoff) + ldsw), 16, 0, 0); \
;         __builtin_amdgcn_global_load_lds((const unsigned*)((const char*)(gbase) + (q) + (off)), (LAS unsigned*)(lds + (bufoff) + ldsw + 8192), 16, 0, 0); } while (0)
; #define PG8_LDA(dst, b, h) do { _Pragma("unroll") for (int m = 0; m < 4; ++m) _Pragma("unroll") for (int k = 0; k < 2; ++k) dst[m][k] = *(const LAS bf16x8*)(lds + PG8_SA(b, h) + aoff + m * 2048 + k * 1024); } while (0)
; #define PG8_LDB(dst, b, h) do { _Pragma("unroll") for (int n = 0; n < 2; ++n) _Pragma("unroll") for (int k = 0; k < 2; ++k) dst[n][k] = *(const LAS bf16x8*)(lds + PG8_SB(b, h) + boff + n * 2048 + k * 1024); } while (0)
; #define PG8_MMA(ai, bj, At, Bt) do { __builtin_amdgcn_s_setprio(1); _Pragma("unroll") for (int m = 0; m < 4; ++m) _Pragma("unroll") for (int n = 0; n < 2; ++n) _Pragma("unroll") for (int k = 0; k < 2; ++k) \
;         acc[ai][bj][m][n] = __builtin_amdgcn_mfma_f32_16x16x32_bf16(Bt[n][k], At[m][k], acc[ai][bj][m][n], 0, 0, 0); __builtin_amdgcn_s_setprio(0); } while (0)
; #define PG8_WAIT_V(n) asm volatile("s_waitcnt vmcnt(" #n ")" ::: "memory")
; #define PG8_WAIT_L(n) asm volatile("s_waitcnt lgkmcnt(" #n ")" ::: "memory")
; #define PG8_BAR __builtin_amdgcn_s_barrier()
; #define PG8_SCHED __builtin_amdgcn_sched_barrier(0)
; template <class Epi, class Sched>
; __device__ __forceinline__ void gemm_phase(LAS unsigned char* lds, const int tid, const Sched& S, const Epi& E) {
;     ...
;             PG8_LDB(B0, 1, 0); PG8_LDB(B1, 1, 1); PG8_SCHED; PG8_LDA(At, 1, 0); PG8_STAGE(PG8_SA(0, 1), a2 + hA2, oA2, qA2);
;             PG8_WAIT_V(8); PG8_WAIT_L(0); PG8_BAR; PG8_MMA(0, 0, At, B0); PG8_MMA(0, 1, At, B1); PG8_BAR; PG8_SCHED;
;             PG8_LDA(At, 1, 1); PG8_STAGE(PG8_SB(1, 0), b3, oB2, qB2); PG8_STAGE(PG8_SB(1, 1), b3 + hB2, oB2, qB2); PG8_STAGE(PG8_SA(1, 0), a3, oA2, qA2);
;             PG8_WAIT_V(8); PG8_WAIT_L(0); PG8_BAR; PG8_MMA(1, 0, At, B0); PG8_MMA(1, 1, At, B1); PG8_BAR; PG8_SCHED;
;         }
	s_setprio 0
	s_add_i32 s10, 0, 0x18000
	s_add_i32 s11, 0, 0x1c000
	ds_read_b128 v[140:143], v133 offset:32768
	ds_read_b128 v[150:153], v133 offset:33792
	ds_read_b128 v[154:157], v133 offset:34816
	ds_read_b128 v[158:161], v133 offset:35840
	ds_read_b128 v[186:189], v133 offset:49152
	ds_read_b128 v[190:193], v133 offset:50176
	ds_read_b128 v[194:197], v133 offset:51200
	ds_read_b128 v[198:201], v133 offset:52224
	s_add_u32 s6, vcc_lo, s58
	s_addc_u32 s7, vcc_hi, s59
	s_mov_b32 m0, s91
	ds_read_b128 v[202:205], v184 offset:32768
	ds_read_b128 v[206:209], v184 offset:33792
	ds_read_b128 v[210:213], v184 offset:34816
	ds_read_b128 v[214:217], v184 offset:35840
	ds_read_b128 v[218:221], v184 offset:36864
	ds_read_b128 v[222:225], v184 offset:37888
	ds_read_b128 v[226:229], v184 offset:38912
	ds_read_b128 v[230:233], v184 offset:39936
	global_load_lds_dwordx4 v136, s[6:7]
	s_add_u32 s6, s6, s64
	s_addc_u32 s7, s7, s65
	s_mov_b32 m0, s93
	s_nop 0
	global_load_lds_dwordx4 v136, s[6:7]
	s_waitcnt vmcnt(8)
	s_waitcnt lgkmcnt(0)
	s_setprio 1
	s_barrier
	v_mfma_f32_16x16x32_bf16 v[126:129], v[140:143], v[202:205], v[126:129]
	v_mfma_f32_16x16x32_bf16 v[122:125], v[154:157], v[202:205], v[122:125]
	v_mfma_f32_16x16x32_bf16 v[110:113], v[140:143], v[210:213], v[110:113]
	v_mfma_f32_16x16x32_bf16 v[106:109], v[154:157], v[210:213], v[106:109]
	v_mfma_f32_16x16x32_bf16 v[94:97], v[140:143], v[218:221], v[94:97]
	v_mfma_f32_16x16x32_bf16 v[90:93], v[154:157], v[218:221], v[90:93]
	v_mfma_f32_16x16x32_bf16 v[78:81], v[140:143], v[226:229], v[78:81]
	v_mfma_f32_16x16x32_bf16 v[74:77], v[154:157], v[226:229], v[74:77]
	v_mfma_f32_16x16x32_bf16 v[126:129], v[150:153], v[206:209], v[126:129]
	v_mfma_f32_16x16x32_bf16 v[122:125], v[158:161], v[206:209], v[122:125]
	v_mfma_f32_16x16x32_bf16 v[110:113], v[150:153], v[214:217], v[110:113]
	v_mfma_f32_16x16x32_bf16 v[106:109], v[158:161], v[214:217], v[106:109]
	v_mfma_f32_16x16x32_bf16 v[94:97], v[150:153], v[222:225], v[94:97]
	v_mfma_f32_16x16x32_bf16 v[90:93], v[158:161], v[222:225], v[90:93]
	v_mfma_f32_16x16x32_bf16 v[78:81], v[150:153], v[230:233], v[78:81]
	v_mfma_f32_16x16x32_bf16 v[74:77], v[158:161], v[230:233], v[74:77]
	v_mfma_f32_16x16x32_bf16 v[118:121], v[186:189], v[202:205], v[118:121]
	v_mfma_f32_16x16x32_bf16 v[114:117], v[194:197], v[202:205], v[114:117]
	v_mfma_f32_16x16x32_bf16 v[102:105], v[186:189], v[210:213], v[102:105]
	v_mfma_f32_16x16x32_bf16 v[98:101], v[194:197], v[210:213], v[98:101]
	v_mfma_f32_16x16x32_bf16 v[86:89], v[186:189], v[218:221], v[86:89]
	v_mfma_f32_16x16x32_bf16 v[82:85], v[194:197], v[218:221], v[82:85]
	v_mfma_f32_16x16x32_bf16 v[70:73], v[186:189], v[226:229], v[70:73]
	v_mfma_f32_16x16x32_bf16 v[66:69], v[194:197], v[226:229], v[66:69]
	v_mfma_f32_16x16x32_bf16 v[118:121], v[190:193], v[206:209], v[118:121]
	v_mfma_f32_16x16x32_bf16 v[114:117], v[198:201], v[206:209], v[114:117]
	v_mfma_f32_16x16x32_bf16 v[102:105], v[190:193], v[214:217], v[102:105]
	v_mfma_f32_16x16x32_bf16 v[98:101], v[198:201], v[214:217], v[98:101]
	v_mfma_f32_16x16x32_bf16 v[86:89], v[190:193], v[222:225], v[86:89]
	v_mfma_f32_16x16x32_bf16 v[82:85], v[198:201], v[222:225], v[82:85]
	v_mfma_f32_16x16x32_bf16 v[70:73], v[190:193], v[230:233], v[70:73]
	v_mfma_f32_16x16x32_bf16 v[66:69], v[198:201], v[230:233], v[66:69]
	s_barrier
	s_setprio 0
	s_add_i32 s6, s10, s47
	s_add_i32 m0, s6, 0xffffff80
	ds_read_b128 v[202:205], v184 offset:49152
	ds_read_b128 v[206:209], v184 offset:50176
	ds_read_b128 v[210:213], v184 offset:51200
	ds_read_b128 v[214:217], v184 offset:52224
	ds_read_b128 v[218:221], v184 offset:53248
	ds_read_b128 v[222:225], v184 offset:54272
	ds_read_b128 v[226:229], v184 offset:55296
	ds_read_b128 v[230:233], v184 offset:56320
	global_load_lds_dwordx4 v0, s[28:29] offset:128
	s_add_i32 m0, s6, 0x1f80
	s_add_i32 s6, s11, s47
	s_ashr_i32 s100, s73, 31
	s_add_u32 s98, s28, s73
	s_addc_u32 s99, s29, s100
	global_load_lds_dwordx4 v0, s[98:99] offset:128
	s_add_i32 m0, s6, 0xffffff80
	s_nop 0
	s_ashr_i32 s101, s19, 31
	s_add_u32 s98, s28, s19
	s_addc_u32 s99, s29, s101
	global_load_lds_dwordx4 v0, s[98:99] offset:128
	s_add_i32 m0, s6, 0x1f80
	s_nop 0
	s_add_u32 s98, s98, s73
	s_addc_u32 s99, s99, s100
	global_load_lds_dwordx4 v0, s[98:99] offset:128
	s_add_i32 m0, s77, 0xffffff80
	s_nop 0
	global_load_lds_dwordx4 v136, vcc offset:128
	s_add_i32 m0, s88, 0xffffff80
	s_nop 0
	s_add_u32 s98, vcc_lo, s64
	s_addc_u32 s99, vcc_hi, s65
	global_load_lds_dwordx4 v136, s[98:99] offset:128
	s_waitcnt vmcnt(8)
	s_waitcnt lgkmcnt(0)
	s_setprio 1
	s_barrier
	v_mfma_f32_16x16x32_bf16 v[62:65], v[140:143], v[202:205], v[62:65]
	v_mfma_f32_16x16x32_bf16 v[58:61], v[154:157], v[202:205], v[58:61]
	v_mfma_f32_16x16x32_bf16 v[46:49], v[140:143], v[210:213], v[46:49]
	v_mfma_f32_16x16x32_bf16 v[42:45], v[154:157], v[210:213], v[42:45]
	v_mfma_f32_16x16x32_bf16 v[30:33], v[140:143], v[218:221], v[30:33]
	v_mfma_f32_16x16x32_bf16 v[26:29], v[154:157], v[218:221], v[26:29]
	v_mfma_f32_16x16x32_bf16 v[14:17], v[140:143], v[226:229], v[14:17]
	v_mfma_f32_16x16x32_bf16 v[10:13], v[154:157], v[226:229], v[10:13]
	v_mfma_f32_16x16x32_bf16 v[62:65], v[150:153], v[206:209], v[62:65]
	v_mfma_f32_16x16x32_bf16 v[58:61], v[158:161], v[206:209], v[58:61]
	v_mfma_f32_16x16x32_bf16 v[46:49], v[150:153], v[214:217], v[46:49]
	v_mfma_f32_16x16x32_bf16 v[42:45], v[158:161], v[214:217], v[42:45]
	v_mfma_f32_16x16x32_bf16 v[30:33], v[150:153], v[222:225], v[30:33]
	v_mfma_f32_16x16x32_bf16 v[26:29], v[158:161], v[222:225], v[26:29]
	v_mfma_f32_16x16x32_bf16 v[14:17], v[150:153], v[230:233], v[14:17]
	v_mfma_f32_16x16x32_bf16 v[10:13], v[158:161], v[230:233], v[10:13]
	v_mfma_f32_16x16x32_bf16 v[54:57], v[186:189], v[202:205], v[54:57]
	v_mfma_f32_16x16x32_bf16 v[50:53], v[194:197], v[202:205], v[50:53]
	v_mfma_f32_16x16x32_bf16 v[38:41], v[186:189], v[210:213], v[38:41]
	v_mfma_f32_16x16x32_bf16 v[34:37], v[194:197], v[210:213], v[34:37]
	v_mfma_f32_16x16x32_bf16 v[22:25], v[186:189], v[218:221], v[22:25]
	v_mfma_f32_16x16x32_bf16 v[18:21], v[194:197], v[218:221], v[18:21]
	v_mfma_f32_16x16x32_bf16 v[6:9], v[186:189], v[226:229], v[6:9]
	v_mfma_f32_16x16x32_bf16 v[2:5], v[194:197], v[226:229], v[2:5]
	v_mfma_f32_16x16x32_bf16 v[54:57], v[190:193], v[206:209], v[54:57]
	v_mfma_f32_16x16x32_bf16 v[50:53], v[198:201], v[206:209], v[50:53]
	v_mfma_f32_16x16x32_bf16 v[38:41], v[190:193], v[214:217], v[38:41]
	v_mfma_f32_16x16x32_bf16 v[34:37], v[198:201], v[214:217], v[34:37]
	v_mfma_f32_16x16x32_bf16 v[22:25], v[190:193], v[222:225], v[22:25]
	v_mfma_f32_16x16x32_bf16 v[18:21], v[198:201], v[222:225], v[18:21]
	v_mfma_f32_16x16x32_bf16 v[6:9], v[190:193], v[230:233], v[6:9]
	v_mfma_f32_16x16x32_bf16 v[2:5], v[198:201], v[230:233], v[2:5]
	s_barrier
	s_setprio 0
	s_cmp_ge_i32 s20, s37
	s_cbranch_scc1 .LBB0_177
	s_mov_b32 s17, s20
	s_branch .LBB0_173
